# grid barrier: non-leader workgroups issue their acquire invalidate at arrival (overlaps the wait) instead of after release; XCD leader waits for its own invalidate before releasing
# speedup vs baseline: 1.0195x; 1.0177x over previous
; DI unsigned xb_ld(unsigned* p) { return __hip_atomic_load(p, __ATOMIC_RELAXED, __HIP_MEMORY_SCOPE_AGENT); }
; DI unsigned xb_add(unsigned* p, unsigned v) { return __hip_atomic_fetch_add(p, v, __ATOMIC_RELAXED, __HIP_MEMORY_SCOPE_AGENT); }
; #define XB_SPIN(cond, bar) do { unsigned _sp = 0; while (cond) { __builtin_amdgcn_s_sleep(1); \
;     if ((++_sp & 255u) == 0u) { if (xb_ld(&(bar)[XB_TMO])) break; if (_sp > XB_SPIN_CAP) { atomicAdd(&(bar)[XB_TMO], 1u); break; } } } } while (0)
; template <class BG>
; DI void xcd_barrier_bg(const XcdBarrier b, char* smem, BG bg) {
;     ...
;       __builtin_amdgcn_fence(__ATOMIC_RELEASE, "agent");
;       asm volatile("s_waitcnt vmcnt(0)" ::: "memory");
;       const unsigned og = xb_add(&bar[XB_TOP], 1u);
;       const unsigned tg = og / nx;
;       if (og + 1u == (tg + 1u) * nx) xb_add(&bar[XB_TOPGEN], 1u);
;       else XB_SPIN(xb_ld(&bar[XB_TOPGEN]) == tg, bar);
;       __builtin_amdgcn_fence(__ATOMIC_ACQUIRE, "agent");
;       xb_add(&bar[XB_XGEN(b.x)], 1u);
;       asm volatile("s_waitcnt vmcnt(0)" ::: "memory");
;       *sst = 1u;
.LBB0_48:
	s_or_b64 exec, exec, s[6:7]
	s_mov_b64 s[6:7], exec
	v_mbcnt_lo_u32_b32 v2, s6, 0
	v_mbcnt_hi_u32_b32 v2, s7, v2
	s_mov_b32 s11, 0
	v_cmp_eq_u32_e32 vcc, 0, v2
	s_waitcnt vmcnt(0)
	buffer_inv sc1
	s_waitcnt vmcnt(0)
	s_and_saveexec_b64 s[8:9], vcc
	s_cbranch_execz .LBB0_50
	s_add_i32 s10, s13, 0x900
	s_bcnt1_i32_b64 s6, s[6:7]
	v_lshl_add_u64 v[2:3], s[10:11], 2, v[188:189]
	v_mov_b32_e32 v4, s6
	global_atomic_add v[2:3], v4, off

; DI unsigned xb_ld(unsigned* p) { return __hip_atomic_load(p, __ATOMIC_RELAXED, __HIP_MEMORY_SCOPE_AGENT); }
; template <class BG>
; DI void xcd_barrier_bg(const XcdBarrier b, char* smem, BG bg) {
;     ...
;   __syncthreads();
;   if (*sst == 0u) {
;     bool more = true;
;     unsigned polls = 0u;
;     for (;;) {
;       if (threadIdx.x == 0) {
;         bool rel = xb_ld(&b.bar[XB_XGEN(b.x)]) != mygen;
;         if (!rel && (++polls & 1023u) == 0u) { if (xb_ld(&b.bar[XB_TMO])) rel = true; else if (polls > XB_SPIN_CAP) { atomicAdd(&b.bar[XB_TMO], 1u); rel = true; } }
;         *sst = rel ? 2u : 0u;
;       }
;       __syncthreads();
;       const unsigned stv = *sst;
;       if (stv == 2u) break;
;       if (more) more = bg(); else __builtin_amdgcn_s_sleep(2);
.LBB0_52:
	s_or_b64 exec, exec, s[86:87]
	s_add_i32 s13, 0, 12
	s_mov_b64 s[4:5], src_shared_base
	s_cmp_lg_u32 s13, -1
	s_cselect_b32 s4, s13, 0
	s_cselect_b32 s5, s5, 0
	s_waitcnt lgkmcnt(0)
	v_mov_b32_e32 v2, s4
	v_mov_b32_e32 v3, s5
	s_barrier
	flat_load_dword v2, v[2:3] sc0 sc1
	s_waitcnt vmcnt(0)
	s_mov_b32 s5, 0
	s_waitcnt lgkmcnt(0)
	v_cmp_eq_u32_e32 vcc, 0, v2
	s_and_saveexec_b64 s[14:15], vcc
	s_cbranch_execz .LBB0_102
	v_readfirstlane_b32 s96, v0
	s_cmp_lt_u32 s96, 64
	s_cbranch_scc0 .Lbinv_1
	buffer_inv sc1
.Lbinv_1:
	s_lshl_b32 s4, s33, 6
	s_addk_i32 s4, 0x900
	v_and_b32_e32 v2, 63, v0
	v_lshl_add_u64 v[34:35], s[4:5], 2, v[188:189]
	v_lshlrev_b32_e32 v36, 4, v2
	v_cmp_eq_u32_e64 s[4:5], 0, v2
	v_mbcnt_lo_u32_b32 v2, -1, 0
	v_mbcnt_hi_u32_b32 v49, -1, v2
	s_mov_b64 s[16:17], src_shared_base
	v_mov_b32_e32 v39, 0
	s_add_u32 s18, s82, 0x3b00
	v_and_b32_e32 v2, 64, v49
	v_lshrrev_b32_e32 v48, 6, v0
	v_mov_b32_e32 v37, v39
	s_addc_u32 s19, s83, 0
	s_mov_b64 s[6:7], -1
	s_mov_b64 s[20:21], 0
	s_mov_b32 s16, 0x400000
	s_add_i32 s86, 0, 8
	s_movk_i32 s87, 0x1000
	s_movk_i32 s88, 0xfff
	s_mov_b64 s[22:23], 0x1000
	s_mov_b32 s89, 0x43c00000
	s_mov_b32 s90, 0x800000
	s_movk_i32 s91, 0xff9c
	s_mov_b32 s92, 0x42fe0000
	s_mov_b32 s93, 0x40c0c00
	v_add_u32_e32 v50, 64, v2
	v_xor_b32_e32 v51, 32, v49
	v_xor_b32_e32 v52, 16, v49
	v_xor_b32_e32 v53, 8, v49
	v_xor_b32_e32 v54, 4, v49
	v_xor_b32_e32 v55, 2, v49
	v_xor_b32_e32 v56, 1, v49
	v_lshlrev_b32_e32 v38, 2, v36
	v_mov_b32_e32 v57, 0x42000000
	v_mov_b32_e32 v58, 0x64
	v_mov_b32_e32 v59, 0x16e48000
	v_mov_b32_e32 v60, 0x16e38000
	v_mov_b32_e32 v61, 0x4538000
	v_mov_b32_e32 v62, 0x2538000
	v_mov_b32_e32 v63, v39
	s_branch .LBB0_58

; template <class BG>
; DI void xcd_barrier_bg(const XcdBarrier b, char* smem, BG bg) {
;     ...
;     if (threadIdx.x == 0) {
;       __builtin_amdgcn_fence(__ATOMIC_ACQUIRE, "agent");
;       asm volatile("s_waitcnt vmcnt(0)" ::: "memory");
;     }
;     __syncthreads();
.LBB0_99:
	s_or_b64 exec, exec, s[20:21]
	s_and_b64 exec, exec, s[2:3]
	s_cbranch_execz .LBB0_101
	s_waitcnt vmcnt(0)
.LBB0_101:
	s_barrier

; DI unsigned xb_ld(unsigned* p) { return __hip_atomic_load(p, __ATOMIC_RELAXED, __HIP_MEMORY_SCOPE_AGENT); }
; template <class BG>
; DI void xcd_barrier_bg(const XcdBarrier b, char* smem, BG bg) {
;     ...
;   __syncthreads();
;   if (*sst == 0u) {
;     bool more = true;
;     unsigned polls = 0u;
;     for (;;) {
;       if (threadIdx.x == 0) {
;         bool rel = xb_ld(&b.bar[XB_XGEN(b.x)]) != mygen;
;         if (!rel && (++polls & 1023u) == 0u) { if (xb_ld(&b.bar[XB_TMO])) rel = true; else if (polls > XB_SPIN_CAP) { atomicAdd(&b.bar[XB_TMO], 1u); rel = true; } }
;         *sst = rel ? 2u : 0u;
;       }
;       __syncthreads();
;       const unsigned stv = *sst;
;       if (stv == 2u) break;
;       if (more) more = bg(); else __builtin_amdgcn_s_sleep(2);
.LBB0_224:
	s_or_b64 exec, exec, s[42:43]
	s_add_i32 s13, 0, 12
	s_mov_b64 s[4:5], src_shared_base
	s_cmp_lg_u32 s13, -1
	s_cselect_b32 s4, s13, 0
	s_cselect_b32 s5, s5, 0
	s_waitcnt lgkmcnt(0)
	v_mov_b32_e32 v2, s4
	v_mov_b32_e32 v3, s5
	s_barrier
	flat_load_dword v2, v[2:3] sc0 sc1
	s_waitcnt vmcnt(0)
	s_mov_b32 s5, 0
	s_waitcnt lgkmcnt(0)
	v_cmp_eq_u32_e32 vcc, 0, v2
	s_and_saveexec_b64 s[14:15], vcc
	s_cbranch_execz .LBB0_274
	v_readfirstlane_b32 s96, v0
	s_cmp_lt_u32 s96, 64
	s_cbranch_scc0 .Lbinv_2
	buffer_inv sc1
.Lbinv_2:
	s_lshl_b32 s4, s33, 6
	s_addk_i32 s4, 0x900
	v_and_b32_e32 v2, 63, v0
	v_lshl_add_u64 v[34:35], s[4:5], 2, v[188:189]
	v_lshlrev_b32_e32 v36, 4, v2
	v_cmp_eq_u32_e64 s[4:5], 0, v2
	v_mbcnt_lo_u32_b32 v2, -1, 0
	v_mbcnt_hi_u32_b32 v49, -1, v2
	s_mov_b64 s[16:17], src_shared_base
	v_mov_b32_e32 v39, 0
	s_add_u32 s18, s82, 0x3b00
	v_and_b32_e32 v2, 64, v49
	v_lshrrev_b32_e32 v48, 6, v0
	v_mov_b32_e32 v37, v39
	s_addc_u32 s19, s83, 0
	s_mov_b64 s[6:7], -1
	s_mov_b64 s[20:21], 0
	s_mov_b32 s16, 0x400000
	s_add_i32 s42, 0, 8
	s_movk_i32 s43, 0x1000
	s_movk_i32 s44, 0xfff
	s_mov_b64 s[22:23], 0x1000
	s_mov_b32 s45, 0x43c00000
	s_mov_b32 s46, 0x800000
	s_movk_i32 s47, 0xff9c
	s_mov_b32 s48, 0x42fe0000
	s_mov_b32 s49, 0x40c0c00
	v_add_u32_e32 v50, 64, v2
	v_xor_b32_e32 v51, 32, v49
	v_xor_b32_e32 v52, 16, v49
	v_xor_b32_e32 v53, 8, v49
	v_xor_b32_e32 v54, 4, v49
	v_xor_b32_e32 v55, 2, v49
	v_xor_b32_e32 v56, 1, v49
	v_lshlrev_b32_e32 v38, 2, v36
	v_mov_b32_e32 v57, 0x42000000
	v_mov_b32_e32 v58, 0x64
	v_mov_b32_e32 v59, 0x16e48000
	v_mov_b32_e32 v60, 0x16e38000
	v_mov_b32_e32 v61, 0x4538000
	v_mov_b32_e32 v62, 0x2538000
	v_mov_b32_e32 v63, v39
	s_branch .LBB0_230

; template <class BG>
; DI void xcd_barrier_bg(const XcdBarrier b, char* smem, BG bg) {
;     ...
;     if (threadIdx.x == 0) {
;       __builtin_amdgcn_fence(__ATOMIC_ACQUIRE, "agent");
;       asm volatile("s_waitcnt vmcnt(0)" ::: "memory");
;     }
;     __syncthreads();
.LBB0_271:
	s_or_b64 exec, exec, s[20:21]
	s_and_b64 exec, exec, s[2:3]
	s_cbranch_execz .LBB0_273
	s_waitcnt vmcnt(0)
.LBB0_273:
	s_barrier

; DI unsigned xb_ld(unsigned* p) { return __hip_atomic_load(p, __ATOMIC_RELAXED, __HIP_MEMORY_SCOPE_AGENT); }
; template <class BG>
; DI void xcd_barrier_bg(const XcdBarrier b, char* smem, BG bg) {
;     ...
;   __syncthreads();
;   if (*sst == 0u) {
;     bool more = true;
;     unsigned polls = 0u;
;     for (;;) {
;       if (threadIdx.x == 0) {
;         bool rel = xb_ld(&b.bar[XB_XGEN(b.x)]) != mygen;
;         if (!rel && (++polls & 1023u) == 0u) { if (xb_ld(&b.bar[XB_TMO])) rel = true; else if (polls > XB_SPIN_CAP) { atomicAdd(&b.bar[XB_TMO], 1u); rel = true; } }
;         *sst = rel ? 2u : 0u;
;       }
;       __syncthreads();
;       const unsigned stv = *sst;
;       if (stv == 2u) break;
;       if (more) more = bg(); else __builtin_amdgcn_s_sleep(2);
.LBB0_331:
	s_or_b64 exec, exec, s[40:41]
	s_add_i32 s13, 0, 12
	s_mov_b64 s[4:5], src_shared_base
	s_cmp_lg_u32 s13, -1
	s_cselect_b32 s4, s13, 0
	s_cselect_b32 s5, s5, 0
	s_waitcnt lgkmcnt(0)
	v_mov_b32_e32 v2, s4
	v_mov_b32_e32 v3, s5
	s_barrier
	flat_load_dword v2, v[2:3] sc0 sc1
	s_waitcnt vmcnt(0)
	s_mov_b32 s5, 0
	s_waitcnt lgkmcnt(0)
	v_cmp_eq_u32_e32 vcc, 0, v2
	s_and_saveexec_b64 s[14:15], vcc
	s_cbranch_execz .LBB0_381
	v_readfirstlane_b32 s96, v0
	s_cmp_lt_u32 s96, 64
	s_cbranch_scc0 .Lbinv_3
	buffer_inv sc1
.Lbinv_3:
	s_lshl_b32 s4, s33, 6
	s_addk_i32 s4, 0x900
	v_and_b32_e32 v2, 63, v0
	v_lshl_add_u64 v[34:35], s[4:5], 2, v[188:189]
	v_lshlrev_b32_e32 v36, 4, v2
	v_cmp_eq_u32_e64 s[4:5], 0, v2
	v_mbcnt_lo_u32_b32 v2, -1, 0
	v_mbcnt_hi_u32_b32 v49, -1, v2
	s_mov_b64 s[16:17], src_shared_base
	v_mov_b32_e32 v39, 0
	s_add_u32 s18, s82, 0x3b00
	v_and_b32_e32 v2, 64, v49
	v_lshrrev_b32_e32 v48, 6, v0
	v_mov_b32_e32 v37, v39
	s_addc_u32 s19, s83, 0
	s_mov_b64 s[6:7], -1
	s_mov_b64 s[20:21], 0
	s_mov_b32 s16, 0x400000
	s_add_i32 s40, 0, 8
	s_movk_i32 s41, 0x1000
	s_movk_i32 s44, 0xfff
	s_mov_b64 s[22:23], 0x1000
	s_mov_b32 s45, 0x43c00000
	s_mov_b32 s46, 0x800000
	s_movk_i32 s47, 0xff9c
	s_mov_b32 s48, 0x42fe0000
	s_mov_b32 s49, 0x40c0c00
	v_add_u32_e32 v50, 64, v2
	v_xor_b32_e32 v51, 32, v49
	v_xor_b32_e32 v52, 16, v49
	v_xor_b32_e32 v53, 8, v49
	v_xor_b32_e32 v54, 4, v49
	v_xor_b32_e32 v55, 2, v49
	v_xor_b32_e32 v56, 1, v49
	v_lshlrev_b32_e32 v38, 2, v36
	v_mov_b32_e32 v57, 0x42000000
	v_mov_b32_e32 v58, 0x64
	v_mov_b32_e32 v59, 0x16e48000
	v_mov_b32_e32 v60, 0x16e38000
	v_mov_b32_e32 v61, 0x4538000
	v_mov_b32_e32 v62, 0x2538000
	v_mov_b32_e32 v63, v39
	s_branch .LBB0_337

; template <class BG>
; DI void xcd_barrier_bg(const XcdBarrier b, char* smem, BG bg) {
;     ...
;     if (threadIdx.x == 0) {
;       __builtin_amdgcn_fence(__ATOMIC_ACQUIRE, "agent");
;       asm volatile("s_waitcnt vmcnt(0)" ::: "memory");
;     }
;     __syncthreads();
.LBB0_378:
	s_or_b64 exec, exec, s[20:21]
	s_and_b64 exec, exec, s[2:3]
	s_cbranch_execz .LBB0_380
	s_waitcnt vmcnt(0)
.LBB0_380:
	s_barrier

; template <class BG>
; DI void xcd_barrier_bg(const XcdBarrier b, char* smem, BG bg) {
;     ...
;     if (threadIdx.x == 0) {
;       __builtin_amdgcn_fence(__ATOMIC_ACQUIRE, "agent");
;       asm volatile("s_waitcnt vmcnt(0)" ::: "memory");
;     }
;     __syncthreads();
.LBB0_487:
	s_or_b64 exec, exec, s[20:21]
	s_and_b64 exec, exec, s[2:3]
	s_cbranch_execz .LBB0_489
	s_waitcnt vmcnt(0)
.LBB0_489:
	s_barrier

; template <class BG>
; DI void xcd_barrier_bg(const XcdBarrier b, char* smem, BG bg) {
;     ...
;     if (threadIdx.x == 0) {
;       __builtin_amdgcn_fence(__ATOMIC_ACQUIRE, "agent");
;       asm volatile("s_waitcnt vmcnt(0)" ::: "memory");
;     }
;     __syncthreads();
.LBB0_624:
	s_or_b64 exec, exec, s[20:21]
	s_and_b64 exec, exec, s[2:3]
	s_cbranch_execz .LBB0_626
	s_waitcnt vmcnt(0)
.LBB0_626:
	s_barrier

; template <class BG>
; DI void xcd_barrier_bg(const XcdBarrier b, char* smem, BG bg) {
;     ...
;     if (threadIdx.x == 0) {
;       __builtin_amdgcn_fence(__ATOMIC_ACQUIRE, "agent");
;       asm volatile("s_waitcnt vmcnt(0)" ::: "memory");
;     }
;     __syncthreads();
.LBB0_739:
	s_or_b64 exec, exec, s[20:21]
	s_and_b64 exec, exec, s[2:3]
	s_cbranch_execz .LBB0_741
	s_waitcnt vmcnt(0)
.LBB0_741:
	s_barrier

; template <class BG>
; DI void xcd_barrier_bg(const XcdBarrier b, char* smem, BG bg) {
;     ...
;     if (threadIdx.x == 0) {
;       __builtin_amdgcn_fence(__ATOMIC_ACQUIRE, "agent");
;       asm volatile("s_waitcnt vmcnt(0)" ::: "memory");
;     }
;     __syncthreads();
.LBB0_845:
	s_or_b64 exec, exec, s[20:21]
	s_and_b64 exec, exec, s[2:3]
	s_cbranch_execz .LBB0_847
	s_waitcnt vmcnt(0)
.LBB0_847:
	s_barrier

; template <class BG>
; DI void xcd_barrier_bg(const XcdBarrier b, char* smem, BG bg) {
;     ...
;     if (threadIdx.x == 0) {
;       __builtin_amdgcn_fence(__ATOMIC_ACQUIRE, "agent");
;       asm volatile("s_waitcnt vmcnt(0)" ::: "memory");
;     }
;     __syncthreads();
.LBB0_944:
	s_or_b64 exec, exec, s[20:21]
	s_and_b64 exec, exec, s[2:3]
	s_cbranch_execz .LBB0_946
	s_waitcnt vmcnt(0)
.LBB0_946:
	s_barrier

; DI unsigned xb_ld(unsigned* p) { return __hip_atomic_load(p, __ATOMIC_RELAXED, __HIP_MEMORY_SCOPE_AGENT); }
; DI unsigned xb_add(unsigned* p, unsigned v) { return __hip_atomic_fetch_add(p, v, __ATOMIC_RELAXED, __HIP_MEMORY_SCOPE_AGENT); }
; #define XB_SPIN(cond, bar) do { unsigned _sp = 0; while (cond) { __builtin_amdgcn_s_sleep(1); \
;     if ((++_sp & 255u) == 0u) { if (xb_ld(&(bar)[XB_TMO])) break; if (_sp > XB_SPIN_CAP) { atomicAdd(&(bar)[XB_TMO], 1u); break; } } } } while (0)
; DI void xcd_barrier(const XcdBarrier& b) {
;     ...
;     const unsigned old = xb_add(&bar[XB_XSUB(b.x)], 1u);
;     const unsigned gen = old / nloc;
;     if (old + 1u == (gen + 1u) * nloc) {
;       __builtin_amdgcn_fence(__ATOMIC_RELEASE, "agent");
;       asm volatile("s_waitcnt vmcnt(0)" ::: "memory");
;       const unsigned og = xb_add(&bar[XB_TOP], 1u);
;       const unsigned tg = og / nx;
;       if (og + 1u == (tg + 1u) * nx) xb_add(&bar[XB_TOPGEN], 1u);
;       else XB_SPIN(xb_ld(&bar[XB_TOPGEN]) == tg, bar);
;       __builtin_amdgcn_fence(__ATOMIC_ACQUIRE, "agent");
;       xb_add(&bar[XB_XGEN(b.x)], 1u);
;       asm volatile("s_waitcnt vmcnt(0)" ::: "memory");
;     } else {
;       XB_SPIN(xb_ld(&bar[XB_XGEN(b.x)]) == gen, bar);
.LBB0_1013:
	s_or_b64 exec, exec, s[4:5]
	v_cvt_f32_u32_e32 v5, v4
	s_waitcnt vmcnt(0)
	v_readfirstlane_b32 s2, v3
	v_rcp_iflag_f32_e32 v5, v5
	s_nop 0
	v_add_u32_e32 v1, s2, v1
	v_add_u32_e32 v6, 1, v1
	v_mul_f32_e32 v3, 0x4f7ffffe, v5
	v_cvt_u32_f32_e32 v3, v3
	v_sub_u32_e32 v5, 0, v4
	v_mul_lo_u32 v5, v5, v3
	v_mul_hi_u32 v5, v3, v5
	v_add_u32_e32 v3, v3, v5
	v_mul_hi_u32 v3, v1, v3
	v_mul_lo_u32 v5, v3, v4
	v_sub_u32_e32 v1, v1, v5
	v_add_u32_e32 v7, 1, v3
	v_cmp_ge_u32_e32 vcc, v1, v4
	v_sub_u32_e32 v5, v1, v4
	s_nop 0
	v_cndmask_b32_e32 v3, v3, v7, vcc
	v_cndmask_b32_e32 v1, v1, v5, vcc
	v_add_u32_e32 v5, 1, v3
	v_cmp_ge_u32_e32 vcc, v1, v4
	s_nop 1
	v_cndmask_b32_e32 v1, v3, v5, vcc
	v_mad_u64_u32 v[4:5], s[2:3], v4, v1, v[4:5]
	v_cmp_ne_u32_e32 vcc, v6, v4
	s_and_saveexec_b64 s[2:3], vcc
	s_xor_b64 s[2:3], exec, s[2:3]
	s_cbranch_execz .LBB0_1027
	s_add_i32 s4, s13, 0x900
	s_mov_b32 s5, 0
	s_waitcnt lgkmcnt(0)
	v_lshl_add_u64 v[2:3], s[4:5], 2, v[188:189]
	buffer_inv sc1
	global_load_dword v4, v[2:3], off sc1
	s_waitcnt vmcnt(0)
	v_cmp_eq_u32_e32 vcc, v4, v1
	s_and_saveexec_b64 s[4:5], vcc
	s_cbranch_execz .LBB0_1026
	s_mov_b32 s22, 1
	s_mov_b64 s[6:7], 0
	s_branch .LBB0_1017

; DI unsigned xb_ld(unsigned* p) { return __hip_atomic_load(p, __ATOMIC_RELAXED, __HIP_MEMORY_SCOPE_AGENT); }
; DI unsigned xb_add(unsigned* p, unsigned v) { return __hip_atomic_fetch_add(p, v, __ATOMIC_RELAXED, __HIP_MEMORY_SCOPE_AGENT); }
; #define XB_SPIN(cond, bar) do { unsigned _sp = 0; while (cond) { __builtin_amdgcn_s_sleep(1); \
;     if ((++_sp & 255u) == 0u) { if (xb_ld(&(bar)[XB_TMO])) break; if (_sp > XB_SPIN_CAP) { atomicAdd(&(bar)[XB_TMO], 1u); break; } } } } while (0)
; DI void xcd_barrier(const XcdBarrier& b) {
;     ...
;     if (old + 1u == (gen + 1u) * nloc) {
;       __builtin_amdgcn_fence(__ATOMIC_RELEASE, "agent");
;       asm volatile("s_waitcnt vmcnt(0)" ::: "memory");
;       const unsigned og = xb_add(&bar[XB_TOP], 1u);
;       const unsigned tg = og / nx;
;       if (og + 1u == (tg + 1u) * nx) xb_add(&bar[XB_TOPGEN], 1u);
;       else XB_SPIN(xb_ld(&bar[XB_TOPGEN]) == tg, bar);
;       __builtin_amdgcn_fence(__ATOMIC_ACQUIRE, "agent");
;       xb_add(&bar[XB_XGEN(b.x)], 1u);
;       asm volatile("s_waitcnt vmcnt(0)" ::: "memory");
;     } else {
;       XB_SPIN(xb_ld(&bar[XB_XGEN(b.x)]) == gen, bar);
;       __builtin_amdgcn_fence(__ATOMIC_ACQUIRE, "agent");
;       asm volatile("s_waitcnt vmcnt(0)" ::: "memory");
.LBB0_1026:
	s_or_b64 exec, exec, s[4:5]
	s_waitcnt vmcnt(0)
.LBB0_1027:
	s_andn2_saveexec_b64 s[2:3], s[2:3]
	s_cbranch_execz .LBB0_1047
	s_mov_b64 s[4:5], exec
	buffer_wbl2 sc1
	s_waitcnt lgkmcnt(0)
	s_waitcnt vmcnt(0)
	v_mbcnt_lo_u32_b32 v1, s4, 0
	v_mbcnt_hi_u32_b32 v1, s5, v1
	v_cmp_eq_u32_e32 vcc, 0, v1
	s_and_saveexec_b64 s[2:3], vcc
	s_cbranch_execz .LBB0_1030
	s_bcnt1_i32_b64 s4, s[4:5]
	v_add_co_u32_e32 v4, vcc, 0x3000, v188
	v_mov_b32_e32 v3, s4
	s_nop 0
	v_addc_co_u32_e32 v5, vcc, 0, v189, vcc
	global_atomic_add v3, v[4:5], v3, off offset:1024 sc0

; DI unsigned xb_ld(unsigned* p) { return __hip_atomic_load(p, __ATOMIC_RELAXED, __HIP_MEMORY_SCOPE_AGENT); }
; DI unsigned xb_add(unsigned* p, unsigned v) { return __hip_atomic_fetch_add(p, v, __ATOMIC_RELAXED, __HIP_MEMORY_SCOPE_AGENT); }
; #define XB_SPIN(cond, bar) do { unsigned _sp = 0; while (cond) { __builtin_amdgcn_s_sleep(1); \
;     if ((++_sp & 255u) == 0u) { if (xb_ld(&(bar)[XB_TMO])) break; if (_sp > XB_SPIN_CAP) { atomicAdd(&(bar)[XB_TMO], 1u); break; } } } } while (0)
; DI void xcd_barrier(const XcdBarrier& b) {
;     ...
;       const unsigned og = xb_add(&bar[XB_TOP], 1u);
;       const unsigned tg = og / nx;
;       if (og + 1u == (tg + 1u) * nx) xb_add(&bar[XB_TOPGEN], 1u);
;       else XB_SPIN(xb_ld(&bar[XB_TOPGEN]) == tg, bar);
;       __builtin_amdgcn_fence(__ATOMIC_ACQUIRE, "agent");
;       xb_add(&bar[XB_XGEN(b.x)], 1u);
;       asm volatile("s_waitcnt vmcnt(0)" ::: "memory");
.LBB0_1044:
	s_or_b64 exec, exec, s[2:3]
	s_mov_b64 s[2:3], exec
	v_mbcnt_lo_u32_b32 v1, s2, 0
	v_mbcnt_hi_u32_b32 v1, s3, v1
	s_mov_b32 s7, 0
	v_cmp_eq_u32_e32 vcc, 0, v1
	s_waitcnt vmcnt(0)
	buffer_inv sc1
	s_waitcnt vmcnt(0)
	s_and_saveexec_b64 s[4:5], vcc
	s_cbranch_execz .LBB0_1046
	s_add_i32 s6, s13, 0x900
	s_bcnt1_i32_b64 s2, s[2:3]
	v_lshl_add_u64 v[2:3], s[6:7], 2, v[188:189]
	v_mov_b32_e32 v1, s2
	global_atomic_add v[2:3], v1, off

; DI unsigned xb_ld(unsigned* p) { return __hip_atomic_load(p, __ATOMIC_RELAXED, __HIP_MEMORY_SCOPE_AGENT); }
; DI unsigned xb_add(unsigned* p, unsigned v) { return __hip_atomic_fetch_add(p, v, __ATOMIC_RELAXED, __HIP_MEMORY_SCOPE_AGENT); }
; #define XB_SPIN(cond, bar) do { unsigned _sp = 0; while (cond) { __builtin_amdgcn_s_sleep(1); \
;     if ((++_sp & 255u) == 0u) { if (xb_ld(&(bar)[XB_TMO])) break; if (_sp > XB_SPIN_CAP) { atomicAdd(&(bar)[XB_TMO], 1u); break; } } } } while (0)
; DI void xcd_barrier(const XcdBarrier& b) {
;     ...
;     if (old + 1u == (gen + 1u) * nloc) {
;       __builtin_amdgcn_fence(__ATOMIC_RELEASE, "agent");
;       asm volatile("s_waitcnt vmcnt(0)" ::: "memory");
;       const unsigned og = xb_add(&bar[XB_TOP], 1u);
;       const unsigned tg = og / nx;
;       if (og + 1u == (tg + 1u) * nx) xb_add(&bar[XB_TOPGEN], 1u);
;       else XB_SPIN(xb_ld(&bar[XB_TOPGEN]) == tg, bar);
;       __builtin_amdgcn_fence(__ATOMIC_ACQUIRE, "agent");
;       xb_add(&bar[XB_XGEN(b.x)], 1u);
;       asm volatile("s_waitcnt vmcnt(0)" ::: "memory");
;     } else {
;       XB_SPIN(xb_ld(&bar[XB_XGEN(b.x)]) == gen, bar);
;       __builtin_amdgcn_fence(__ATOMIC_ACQUIRE, "agent");
;       asm volatile("s_waitcnt vmcnt(0)" ::: "memory");
.LBB0_1095:
	s_or_b64 exec, exec, s[4:5]
	s_waitcnt vmcnt(0)
.LBB0_1096:
	s_andn2_saveexec_b64 s[2:3], s[2:3]
	s_cbranch_execz .LBB0_1116
	s_mov_b64 s[4:5], exec
	buffer_wbl2 sc1
	s_waitcnt lgkmcnt(0)
	s_waitcnt vmcnt(0)
	v_mbcnt_lo_u32_b32 v1, s4, 0
	v_mbcnt_hi_u32_b32 v1, s5, v1
	v_cmp_eq_u32_e32 vcc, 0, v1
	s_and_saveexec_b64 s[2:3], vcc
	s_cbranch_execz .LBB0_1099
	s_bcnt1_i32_b64 s4, s[4:5]
	v_add_co_u32_e32 v4, vcc, 0x3000, v188
	v_mov_b32_e32 v3, s4
	s_nop 0
	v_addc_co_u32_e32 v5, vcc, 0, v189, vcc
	global_atomic_add v3, v[4:5], v3, off offset:1024 sc0

; DI unsigned xb_ld(unsigned* p) { return __hip_atomic_load(p, __ATOMIC_RELAXED, __HIP_MEMORY_SCOPE_AGENT); }
; DI unsigned xb_add(unsigned* p, unsigned v) { return __hip_atomic_fetch_add(p, v, __ATOMIC_RELAXED, __HIP_MEMORY_SCOPE_AGENT); }
; #define XB_SPIN(cond, bar) do { unsigned _sp = 0; while (cond) { __builtin_amdgcn_s_sleep(1); \
;     if ((++_sp & 255u) == 0u) { if (xb_ld(&(bar)[XB_TMO])) break; if (_sp > XB_SPIN_CAP) { atomicAdd(&(bar)[XB_TMO], 1u); break; } } } } while (0)
; DI void xcd_barrier(const XcdBarrier& b) {
;     ...
;     if (old + 1u == (gen + 1u) * nloc) {
;       __builtin_amdgcn_fence(__ATOMIC_RELEASE, "agent");
;       asm volatile("s_waitcnt vmcnt(0)" ::: "memory");
;       const unsigned og = xb_add(&bar[XB_TOP], 1u);
;       const unsigned tg = og / nx;
;       if (og + 1u == (tg + 1u) * nx) xb_add(&bar[XB_TOPGEN], 1u);
;       else XB_SPIN(xb_ld(&bar[XB_TOPGEN]) == tg, bar);
;       __builtin_amdgcn_fence(__ATOMIC_ACQUIRE, "agent");
;       xb_add(&bar[XB_XGEN(b.x)], 1u);
;       asm volatile("s_waitcnt vmcnt(0)" ::: "memory");
;     } else {
;       XB_SPIN(xb_ld(&bar[XB_XGEN(b.x)]) == gen, bar);
;       __builtin_amdgcn_fence(__ATOMIC_ACQUIRE, "agent");
;       asm volatile("s_waitcnt vmcnt(0)" ::: "memory");
.LBB0_1165:
	s_or_b64 exec, exec, s[4:5]
	s_waitcnt vmcnt(0)
.LBB0_1166:
	s_andn2_saveexec_b64 s[2:3], s[2:3]
	s_cbranch_execz .LBB0_1186
	s_mov_b64 s[4:5], exec
	buffer_wbl2 sc1
	s_waitcnt lgkmcnt(0)
	s_waitcnt vmcnt(0)
	v_mbcnt_lo_u32_b32 v1, s4, 0
	v_mbcnt_hi_u32_b32 v1, s5, v1
	v_cmp_eq_u32_e32 vcc, 0, v1
	s_and_saveexec_b64 s[2:3], vcc
	s_cbranch_execz .LBB0_1169
	s_bcnt1_i32_b64 s4, s[4:5]
	v_add_co_u32_e32 v4, vcc, 0x3000, v188
	v_mov_b32_e32 v3, s4
	s_nop 0
	v_addc_co_u32_e32 v5, vcc, 0, v189, vcc
	global_atomic_add v3, v[4:5], v3, off offset:1024 sc0

; DI unsigned xb_ld(unsigned* p) { return __hip_atomic_load(p, __ATOMIC_RELAXED, __HIP_MEMORY_SCOPE_AGENT); }
; DI unsigned xb_add(unsigned* p, unsigned v) { return __hip_atomic_fetch_add(p, v, __ATOMIC_RELAXED, __HIP_MEMORY_SCOPE_AGENT); }
; #define XB_SPIN(cond, bar) do { unsigned _sp = 0; while (cond) { __builtin_amdgcn_s_sleep(1); \
;     if ((++_sp & 255u) == 0u) { if (xb_ld(&(bar)[XB_TMO])) break; if (_sp > XB_SPIN_CAP) { atomicAdd(&(bar)[XB_TMO], 1u); break; } } } } while (0)
; DI void xcd_barrier(const XcdBarrier& b) {
;     ...
;     if (old + 1u == (gen + 1u) * nloc) {
;       __builtin_amdgcn_fence(__ATOMIC_RELEASE, "agent");
;       asm volatile("s_waitcnt vmcnt(0)" ::: "memory");
;       const unsigned og = xb_add(&bar[XB_TOP], 1u);
;       const unsigned tg = og / nx;
;       if (og + 1u == (tg + 1u) * nx) xb_add(&bar[XB_TOPGEN], 1u);
;       else XB_SPIN(xb_ld(&bar[XB_TOPGEN]) == tg, bar);
;       __builtin_amdgcn_fence(__ATOMIC_ACQUIRE, "agent");
;       xb_add(&bar[XB_XGEN(b.x)], 1u);
;       asm volatile("s_waitcnt vmcnt(0)" ::: "memory");
;     } else {
;       XB_SPIN(xb_ld(&bar[XB_XGEN(b.x)]) == gen, bar);
;       __builtin_amdgcn_fence(__ATOMIC_ACQUIRE, "agent");
;       asm volatile("s_waitcnt vmcnt(0)" ::: "memory");
.LBB0_1231:
	s_or_b64 exec, exec, s[4:5]
	s_waitcnt vmcnt(0)
.LBB0_1232:
	s_andn2_saveexec_b64 s[2:3], s[2:3]
	s_cbranch_execz .LBB0_1252
	s_mov_b64 s[4:5], exec
	buffer_wbl2 sc1
	s_waitcnt lgkmcnt(0)
	s_waitcnt vmcnt(0)
	v_mbcnt_lo_u32_b32 v1, s4, 0
	v_mbcnt_hi_u32_b32 v1, s5, v1
	v_cmp_eq_u32_e32 vcc, 0, v1
	s_and_saveexec_b64 s[2:3], vcc
	s_cbranch_execz .LBB0_1235
	s_bcnt1_i32_b64 s4, s[4:5]
	v_add_co_u32_e32 v4, vcc, 0x3000, v188
	v_mov_b32_e32 v3, s4
	s_nop 0
	v_addc_co_u32_e32 v5, vcc, 0, v189, vcc
	global_atomic_add v3, v[4:5], v3, off offset:1024 sc0

; DI unsigned xb_ld(unsigned* p) { return __hip_atomic_load(p, __ATOMIC_RELAXED, __HIP_MEMORY_SCOPE_AGENT); }
; DI unsigned xb_add(unsigned* p, unsigned v) { return __hip_atomic_fetch_add(p, v, __ATOMIC_RELAXED, __HIP_MEMORY_SCOPE_AGENT); }
; #define XB_SPIN(cond, bar) do { unsigned _sp = 0; while (cond) { __builtin_amdgcn_s_sleep(1); \
;     if ((++_sp & 255u) == 0u) { if (xb_ld(&(bar)[XB_TMO])) break; if (_sp > XB_SPIN_CAP) { atomicAdd(&(bar)[XB_TMO], 1u); break; } } } } while (0)
; DI void xcd_barrier(const XcdBarrier& b) {
;     ...
;     if (old + 1u == (gen + 1u) * nloc) {
;       __builtin_amdgcn_fence(__ATOMIC_RELEASE, "agent");
;       asm volatile("s_waitcnt vmcnt(0)" ::: "memory");
;       const unsigned og = xb_add(&bar[XB_TOP], 1u);
;       const unsigned tg = og / nx;
;       if (og + 1u == (tg + 1u) * nx) xb_add(&bar[XB_TOPGEN], 1u);
;       else XB_SPIN(xb_ld(&bar[XB_TOPGEN]) == tg, bar);
;       __builtin_amdgcn_fence(__ATOMIC_ACQUIRE, "agent");
;       xb_add(&bar[XB_XGEN(b.x)], 1u);
;       asm volatile("s_waitcnt vmcnt(0)" ::: "memory");
;     } else {
;       XB_SPIN(xb_ld(&bar[XB_XGEN(b.x)]) == gen, bar);
;       __builtin_amdgcn_fence(__ATOMIC_ACQUIRE, "agent");
;       asm volatile("s_waitcnt vmcnt(0)" ::: "memory");
.LBB0_1301:
	s_or_b64 exec, exec, s[4:5]
	s_waitcnt vmcnt(0)
.LBB0_1302:
	s_andn2_saveexec_b64 s[2:3], s[2:3]
	s_cbranch_execz .LBB0_1322
	s_mov_b64 s[4:5], exec
	buffer_wbl2 sc1
	s_waitcnt lgkmcnt(0)
	s_waitcnt vmcnt(0)
	v_mbcnt_lo_u32_b32 v1, s4, 0
	v_mbcnt_hi_u32_b32 v1, s5, v1
	v_cmp_eq_u32_e32 vcc, 0, v1
	s_and_saveexec_b64 s[2:3], vcc
	s_cbranch_execz .LBB0_1305
	s_bcnt1_i32_b64 s4, s[4:5]
	v_add_co_u32_e32 v4, vcc, 0x3000, v188
	v_mov_b32_e32 v3, s4
	s_nop 0
	v_addc_co_u32_e32 v5, vcc, 0, v189, vcc
	global_atomic_add v3, v[4:5], v3, off offset:1024 sc0
